# band item: gate loads hoisted (16 in flight), Q loads batched, vmcnt(0) before PV removed
# speedup vs baseline: 1.0036x; 1.0036x over previous
; __device__ __forceinline__ unsigned cvt_pk_bf16(float lo, float hi) { const f32x2 f = {lo, hi}; const bf16x2_t v = __builtin_convertvector(f, bf16x2_t); return __builtin_bit_cast(unsigned, v); }
; __device__ __forceinline__ float bflo(unsigned u) { return __uint_as_float(u << 16); }
; __device__ __forceinline__ float bfhi(unsigned u) { return __uint_as_float(u & 0xffff0000u); }
; __device__ __forceinline__ float rcp_f(float v) { return __builtin_amdgcn_rcpf(v); }
; __device__ __forceinline__ float silu_f(float v) { return v * rcp_f(1.f + __expf(-v)); }
; __device__ __forceinline__ void b_item(const Params& P, int layer, LAS unsigned char* lds, int item, int tid) {
;     ...
;     __syncthreads();
;     ...
; #pragma unroll
;     for (int u = 0; u < 2; ++u) {
;         float l = lrun[u]; l += __shfl_xor(l, 16); l += __shfl_xor(l, 32);
;         const float inv = rcp_f(l);
;         const size_t tok = tok0 + 64 * qc + 32 * th + 16 * u + c15;
;         const bf16_t* gate = pjp(proj, BG, 128, h, tok);
;         bf16_t* y = (bf16_t*)(P.ws + (layer == 0 ? WS_H : WS_D1)) + tok * DM + YB + h * 128;
; #pragma unroll
;         for (int vb = 0; vb < 8; ++vb) { const int v0 = 16 * vb + 4 * g; const u32x2 gt2 = *(const u32x2*)(gate + v0);
;             u32x2 o; o.x = cvt_pk_bf16(acco[u][vb][0] * inv * silu_f(bflo(gt2.x)), acco[u][vb][1] * inv * silu_f(bfhi(gt2.x)));
;             o.y = cvt_pk_bf16(acco[u][vb][2] * inv * silu_f(bflo(gt2.y)), acco[u][vb][3] * inv * silu_f(bfhi(gt2.y)));
;             *(u32x2*)(y + v0) = o; }
.LBB0_140:
	v_lshl_add_u64 v[64:65], s[50:51], 0, v[152:153]
	v_or_b32_e32 v64, v64, v154
	v_lshl_add_u64 v[66:67], v[64:65], 0, s[12:13]
	v_lshlrev_b64 v[66:67], 8, v[66:67]
	v_lshl_add_u64 v[70:71], v[156:157], 0, v[66:67]
	s_waitcnt vmcnt(0) lgkmcnt(0)
	s_barrier
	v_or_b32_e32 v250, 16, v64
	v_mov_b32_e32 v251, v65
	v_lshl_add_u64 v[250:251], v[250:251], 0, s[12:13]
	v_lshlrev_b64 v[250:251], 8, v[250:251]
	v_lshl_add_u64 v[250:251], v[156:157], 0, v[250:251]
	global_load_dwordx2 v[84:85], v[70:71], off
	global_load_dwordx2 v[86:87], v[70:71], off offset:32
	global_load_dwordx2 v[88:89], v[70:71], off offset:64
	global_load_dwordx2 v[90:91], v[70:71], off offset:96
	global_load_dwordx2 v[92:93], v[70:71], off offset:128
	global_load_dwordx2 v[94:95], v[70:71], off offset:160
	global_load_dwordx2 v[164:165], v[70:71], off offset:192
	global_load_dwordx2 v[166:167], v[70:71], off offset:224
	global_load_dwordx2 v[168:169], v[250:251], off
	global_load_dwordx2 v[170:171], v[250:251], off offset:32
	global_load_dwordx2 v[172:173], v[250:251], off offset:64
	global_load_dwordx2 v[174:175], v[250:251], off offset:96
	global_load_dwordx2 v[252:253], v[250:251], off offset:128
	global_load_dwordx2 v[254:255], v[250:251], off offset:160
	global_load_dwordx2 v[226:227], v[250:251], off offset:192
	global_load_dwordx2 v[250:251], v[250:251], off offset:224
	v_and_b32_e32 v67, 64, v184
	v_xor_b32_e32 v66, 16, v184
	v_add_u32_e32 v67, 64, v67
	v_cmp_lt_i32_e32 vcc, v66, v67
	v_xor_b32_e32 v68, 32, v184
	s_lshl_b32 s0, s10, 7
	v_cndmask_b32_e32 v66, v184, v66, vcc
	v_lshlrev_b32_e32 v69, 2, v66
	ds_bpermute_b32 v73, v69, v225
	v_cmp_lt_i32_e32 vcc, v68, v67
	s_ashr_i32 s1, s0, 31
	v_lshlrev_b64 v[66:67], 12, v[64:65]
	v_cndmask_b32_e32 v68, v184, v68, vcc
	v_lshlrev_b32_e32 v72, 2, v68
	s_waitcnt lgkmcnt(0)
	v_add_f32_e32 v68, v225, v73
	ds_bpermute_b32 v73, v72, v68
	s_lshl_b64 s[0:1], s[0:1], 1
	v_lshl_add_u64 v[66:67], s[18:19], 0, v[66:67]
	v_lshl_add_u64 v[66:67], v[66:67], 0, s[0:1]
	v_lshl_add_u64 v[66:67], v[66:67], 0, v[136:137]
	s_waitcnt lgkmcnt(0)
	v_add_f32_e32 v68, v68, v73
	v_rcp_f32_e32 v68, v68
	v_or_b32_e32 v64, 16, v64
	v_pk_mul_f32 v[60:61], v[60:61], v[68:69] op_sel_hi:[1,0]
	v_pk_mul_f32 v[62:63], v[62:63], v[68:69] op_sel_hi:[1,0]
	v_pk_mul_f32 v[56:57], v[56:57], v[68:69] op_sel_hi:[1,0]
	v_pk_mul_f32 v[58:59], v[58:59], v[68:69] op_sel_hi:[1,0]
	v_pk_mul_f32 v[52:53], v[52:53], v[68:69] op_sel_hi:[1,0]
	v_pk_mul_f32 v[54:55], v[54:55], v[68:69] op_sel_hi:[1,0]
	v_pk_mul_f32 v[48:49], v[48:49], v[68:69] op_sel_hi:[1,0]
	v_pk_mul_f32 v[50:51], v[50:51], v[68:69] op_sel_hi:[1,0]
	v_pk_mul_f32 v[44:45], v[44:45], v[68:69] op_sel_hi:[1,0]
	v_pk_mul_f32 v[46:47], v[46:47], v[68:69] op_sel_hi:[1,0]
	v_pk_mul_f32 v[40:41], v[40:41], v[68:69] op_sel_hi:[1,0]
	v_pk_mul_f32 v[42:43], v[42:43], v[68:69] op_sel_hi:[1,0]
	v_pk_mul_f32 v[36:37], v[36:37], v[68:69] op_sel_hi:[1,0]
	v_pk_mul_f32 v[38:39], v[38:39], v[68:69] op_sel_hi:[1,0]
	v_pk_mul_f32 v[32:33], v[32:33], v[68:69] op_sel_hi:[1,0]
	v_pk_mul_f32 v[34:35], v[34:35], v[68:69] op_sel_hi:[1,0]
	s_waitcnt vmcnt(15)
	v_lshlrev_b32_e32 v76, 16, v84
	v_and_b32_e32 v77, 0xffff0000, v84
	v_lshlrev_b32_e32 v74, 16, v85
	v_and_b32_e32 v75, 0xffff0000, v85
	v_mul_f32_e32 v73, 0xbfb8aa3b, v76
	v_mul_f32_e32 v78, 0xbfb8aa3b, v77
	v_mul_f32_e32 v79, 0xbfb8aa3b, v74
	v_mul_f32_e32 v80, 0xbfb8aa3b, v75
	v_exp_f32_e32 v73, v73
	v_exp_f32_e32 v78, v78
	v_exp_f32_e32 v79, v79
	v_exp_f32_e32 v80, v80
	v_add_f32_e32 v73, 1.0, v73
	v_add_f32_e32 v81, 1.0, v78
	v_add_f32_e32 v82, 1.0, v79
	v_add_f32_e32 v83, 1.0, v80
	v_rcp_f32_e32 v78, v73
	v_rcp_f32_e32 v79, v81
	v_rcp_f32_e32 v80, v82
	v_rcp_f32_e32 v81, v83
	v_pk_mul_f32 v[76:77], v[78:79], v[76:77]
	s_nop 0
	v_pk_mul_f32 v[60:61], v[60:61], v[76:77]
	v_pk_mul_f32 v[74:75], v[80:81], v[74:75]
	v_cvt_pk_bf16_f32 v60, v60, v61
	v_pk_mul_f32 v[62:63], v[62:63], v[74:75]
	s_nop 0
	v_cvt_pk_bf16_f32 v61, v62, v63
	global_store_dwordx2 v[66:67], v[60:61], off offset:1536
	s_waitcnt vmcnt(15)
	v_lshlrev_b32_e32 v62, 16, v86
	v_and_b32_e32 v63, 0xffff0000, v86
	v_lshlrev_b32_e32 v60, 16, v87
	v_and_b32_e32 v61, 0xffff0000, v87
	v_mul_f32_e32 v73, 0xbfb8aa3b, v62
	v_mul_f32_e32 v74, 0xbfb8aa3b, v63
	v_mul_f32_e32 v75, 0xbfb8aa3b, v60
	v_mul_f32_e32 v76, 0xbfb8aa3b, v61
	v_exp_f32_e32 v73, v73
	v_exp_f32_e32 v74, v74
	v_exp_f32_e32 v75, v75
	v_exp_f32_e32 v76, v76
	v_add_f32_e32 v73, 1.0, v73
	v_add_f32_e32 v77, 1.0, v74
	v_add_f32_e32 v78, 1.0, v75
	v_add_f32_e32 v79, 1.0, v76
	v_rcp_f32_e32 v74, v73
	v_rcp_f32_e32 v75, v77
	v_rcp_f32_e32 v76, v78
	v_rcp_f32_e32 v77, v79
	v_pk_mul_f32 v[62:63], v[74:75], v[62:63]
	s_nop 0
	v_pk_mul_f32 v[56:57], v[56:57], v[62:63]
	v_pk_mul_f32 v[60:61], v[76:77], v[60:61]
	v_cvt_pk_bf16_f32 v56, v56, v57
	v_pk_mul_f32 v[58:59], v[58:59], v[60:61]
	s_nop 0
	v_cvt_pk_bf16_f32 v57, v58, v59
	global_store_dwordx2 v[66:67], v[56:57], off offset:1568
	s_waitcnt vmcnt(15)
	v_lshlrev_b32_e32 v58, 16, v88
	v_and_b32_e32 v59, 0xffff0000, v88
	v_lshlrev_b32_e32 v56, 16, v89
	v_and_b32_e32 v57, 0xffff0000, v89
	v_mul_f32_e32 v60, 0xbfb8aa3b, v58
	v_mul_f32_e32 v61, 0xbfb8aa3b, v59
	v_mul_f32_e32 v62, 0xbfb8aa3b, v56
	v_mul_f32_e32 v63, 0xbfb8aa3b, v57
	v_exp_f32_e32 v60, v60
	v_exp_f32_e32 v61, v61
	v_exp_f32_e32 v62, v62
	v_exp_f32_e32 v63, v63
	v_add_f32_e32 v60, 1.0, v60
	v_add_f32_e32 v61, 1.0, v61
	v_add_f32_e32 v62, 1.0, v62
	v_add_f32_e32 v63, 1.0, v63
	v_rcp_f32_e32 v60, v60
	v_rcp_f32_e32 v61, v61
	v_rcp_f32_e32 v62, v62
	v_rcp_f32_e32 v63, v63
	v_pk_mul_f32 v[58:59], v[60:61], v[58:59]
	s_nop 0
	v_pk_mul_f32 v[52:53], v[52:53], v[58:59]
	v_pk_mul_f32 v[56:57], v[62:63], v[56:57]
	v_cvt_pk_bf16_f32 v52, v52, v53
	v_pk_mul_f32 v[54:55], v[54:55], v[56:57]
	s_nop 0
	v_cvt_pk_bf16_f32 v53, v54, v55
	global_store_dwordx2 v[66:67], v[52:53], off offset:1600
	s_waitcnt vmcnt(15)
; __device__ __forceinline__ unsigned cvt_pk_bf16(float lo, float hi) { const f32x2 f = {lo, hi}; const bf16x2_t v = __builtin_convertvector(f, bf16x2_t); return __builtin_bit_cast(unsigned, v); }
; __device__ __forceinline__ float bflo(unsigned u) { return __uint_as_float(u << 16); }
; __device__ __forceinline__ float bfhi(unsigned u) { return __uint_as_float(u & 0xffff0000u); }
; __device__ __forceinline__ float rcp_f(float v) { return __builtin_amdgcn_rcpf(v); }
; __device__ __forceinline__ float silu_f(float v) { return v * rcp_f(1.f + __expf(-v)); }
; __device__ __forceinline__ void b_item(const Params& P, int layer, LAS unsigned char* lds, int item, int tid) {
;     ...
;     for (int u = 0; u < 2; ++u) {
;         float l = lrun[u]; l += __shfl_xor(l, 16); l += __shfl_xor(l, 32);
;         const float inv = rcp_f(l);
;         const size_t tok = tok0 + 64 * qc + 32 * th + 16 * u + c15;
;         const bf16_t* gate = pjp(proj, BG, 128, h, tok);
;         bf16_t* y = (bf16_t*)(P.ws + (layer == 0 ? WS_H : WS_D1)) + tok * DM + YB + h * 128;
; #pragma unroll
;         for (int vb = 0; vb < 8; ++vb) { const int v0 = 16 * vb + 4 * g; const u32x2 gt2 = *(const u32x2*)(gate + v0);
;             u32x2 o; o.x = cvt_pk_bf16(acco[u][vb][0] * inv * silu_f(bflo(gt2.x)), acco[u][vb][1] * inv * silu_f(bfhi(gt2.x)));
;             o.y = cvt_pk_bf16(acco[u][vb][2] * inv * silu_f(bflo(gt2.y)), acco[u][vb][3] * inv * silu_f(bfhi(gt2.y)));
;             *(u32x2*)(y + v0) = o; }
	v_lshlrev_b32_e32 v54, 16, v90
	v_and_b32_e32 v55, 0xffff0000, v90
	v_lshlrev_b32_e32 v52, 16, v91
	v_and_b32_e32 v53, 0xffff0000, v91
	v_mul_f32_e32 v56, 0xbfb8aa3b, v54
	v_mul_f32_e32 v57, 0xbfb8aa3b, v55
	v_mul_f32_e32 v58, 0xbfb8aa3b, v52
	v_mul_f32_e32 v59, 0xbfb8aa3b, v53
	v_exp_f32_e32 v56, v56
	v_exp_f32_e32 v57, v57
	v_exp_f32_e32 v58, v58
	v_exp_f32_e32 v59, v59
	v_add_f32_e32 v56, 1.0, v56
	v_add_f32_e32 v57, 1.0, v57
	v_add_f32_e32 v58, 1.0, v58
	v_add_f32_e32 v59, 1.0, v59
	v_rcp_f32_e32 v56, v56
	v_rcp_f32_e32 v57, v57
	v_rcp_f32_e32 v58, v58
	v_rcp_f32_e32 v59, v59
	v_pk_mul_f32 v[54:55], v[56:57], v[54:55]
	s_nop 0
	v_pk_mul_f32 v[48:49], v[48:49], v[54:55]
	v_pk_mul_f32 v[52:53], v[58:59], v[52:53]
	v_cvt_pk_bf16_f32 v48, v48, v49
	v_pk_mul_f32 v[50:51], v[50:51], v[52:53]
	s_nop 0
	v_cvt_pk_bf16_f32 v49, v50, v51
	global_store_dwordx2 v[66:67], v[48:49], off offset:1632
	s_waitcnt vmcnt(15)
	v_lshlrev_b32_e32 v50, 16, v92
	v_and_b32_e32 v51, 0xffff0000, v92
	v_lshlrev_b32_e32 v48, 16, v93
	v_and_b32_e32 v49, 0xffff0000, v93
	v_mul_f32_e32 v52, 0xbfb8aa3b, v50
	v_mul_f32_e32 v53, 0xbfb8aa3b, v51
	v_mul_f32_e32 v54, 0xbfb8aa3b, v48
	v_mul_f32_e32 v55, 0xbfb8aa3b, v49
	v_exp_f32_e32 v52, v52
	v_exp_f32_e32 v53, v53
	v_exp_f32_e32 v54, v54
	v_exp_f32_e32 v55, v55
	v_add_f32_e32 v52, 1.0, v52
	v_add_f32_e32 v53, 1.0, v53
	v_add_f32_e32 v54, 1.0, v54
	v_add_f32_e32 v55, 1.0, v55
	v_rcp_f32_e32 v52, v52
	v_rcp_f32_e32 v53, v53
	v_rcp_f32_e32 v54, v54
	v_rcp_f32_e32 v55, v55
	v_pk_mul_f32 v[50:51], v[52:53], v[50:51]
	s_nop 0
	v_pk_mul_f32 v[44:45], v[44:45], v[50:51]
	v_pk_mul_f32 v[48:49], v[54:55], v[48:49]
	v_cvt_pk_bf16_f32 v44, v44, v45
	v_pk_mul_f32 v[46:47], v[46:47], v[48:49]
	s_nop 0
	v_cvt_pk_bf16_f32 v45, v46, v47
	global_store_dwordx2 v[66:67], v[44:45], off offset:1664
	s_waitcnt vmcnt(15)
	v_lshlrev_b32_e32 v46, 16, v94
	v_and_b32_e32 v47, 0xffff0000, v94
	v_lshlrev_b32_e32 v44, 16, v95
	v_and_b32_e32 v45, 0xffff0000, v95
	v_mul_f32_e32 v48, 0xbfb8aa3b, v46
	v_mul_f32_e32 v49, 0xbfb8aa3b, v47
	v_mul_f32_e32 v50, 0xbfb8aa3b, v44
	v_mul_f32_e32 v51, 0xbfb8aa3b, v45
	v_exp_f32_e32 v48, v48
	v_exp_f32_e32 v49, v49
	v_exp_f32_e32 v50, v50
	v_exp_f32_e32 v51, v51
	v_add_f32_e32 v48, 1.0, v48
	v_add_f32_e32 v49, 1.0, v49
	v_add_f32_e32 v50, 1.0, v50
	v_add_f32_e32 v51, 1.0, v51
	v_rcp_f32_e32 v48, v48
	v_rcp_f32_e32 v49, v49
	v_rcp_f32_e32 v50, v50
	v_rcp_f32_e32 v51, v51
	v_pk_mul_f32 v[46:47], v[48:49], v[46:47]
	s_nop 0
	v_pk_mul_f32 v[40:41], v[40:41], v[46:47]
	v_pk_mul_f32 v[44:45], v[50:51], v[44:45]
	v_cvt_pk_bf16_f32 v40, v40, v41
	v_pk_mul_f32 v[42:43], v[42:43], v[44:45]
	s_nop 0
	v_cvt_pk_bf16_f32 v41, v42, v43
	global_store_dwordx2 v[66:67], v[40:41], off offset:1696
	s_waitcnt vmcnt(15)
	v_lshlrev_b32_e32 v42, 16, v164
	v_and_b32_e32 v43, 0xffff0000, v164
	v_lshlrev_b32_e32 v40, 16, v165
	v_and_b32_e32 v41, 0xffff0000, v165
	v_mul_f32_e32 v44, 0xbfb8aa3b, v42
	v_mul_f32_e32 v45, 0xbfb8aa3b, v43
	v_mul_f32_e32 v46, 0xbfb8aa3b, v40
	v_mul_f32_e32 v47, 0xbfb8aa3b, v41
	v_exp_f32_e32 v44, v44
	v_exp_f32_e32 v45, v45
	v_exp_f32_e32 v46, v46
	v_exp_f32_e32 v47, v47
	v_add_f32_e32 v44, 1.0, v44
	v_add_f32_e32 v45, 1.0, v45
	v_add_f32_e32 v46, 1.0, v46
	v_add_f32_e32 v47, 1.0, v47
	v_rcp_f32_e32 v44, v44
	v_rcp_f32_e32 v45, v45
	v_rcp_f32_e32 v46, v46
	v_rcp_f32_e32 v47, v47
	v_pk_mul_f32 v[42:43], v[44:45], v[42:43]
	s_nop 0
	v_pk_mul_f32 v[36:37], v[36:37], v[42:43]
	v_pk_mul_f32 v[40:41], v[46:47], v[40:41]
	v_cvt_pk_bf16_f32 v36, v36, v37
	v_pk_mul_f32 v[38:39], v[38:39], v[40:41]
	s_nop 0
	v_cvt_pk_bf16_f32 v37, v38, v39
	global_store_dwordx2 v[66:67], v[36:37], off offset:1728
	v_lshl_add_u64 v[36:37], v[64:65], 0, s[12:13]
	v_lshlrev_b64 v[36:37], 8, v[36:37]
	v_lshl_add_u64 v[36:37], v[156:157], 0, v[36:37]
	s_waitcnt vmcnt(15)
	v_lshlrev_b32_e32 v40, 16, v166
	v_and_b32_e32 v41, 0xffff0000, v166
	v_lshlrev_b32_e32 v38, 16, v167
	v_and_b32_e32 v39, 0xffff0000, v167
	v_mul_f32_e32 v42, 0xbfb8aa3b, v40
	v_mul_f32_e32 v43, 0xbfb8aa3b, v41
	v_mul_f32_e32 v44, 0xbfb8aa3b, v38
	v_mul_f32_e32 v45, 0xbfb8aa3b, v39
	v_exp_f32_e32 v42, v42
	v_exp_f32_e32 v43, v43
	v_exp_f32_e32 v44, v44
	v_exp_f32_e32 v45, v45
	v_add_f32_e32 v42, 1.0, v42
	v_add_f32_e32 v43, 1.0, v43
	v_add_f32_e32 v44, 1.0, v44
	v_add_f32_e32 v45, 1.0, v45
	v_rcp_f32_e32 v42, v42
	v_rcp_f32_e32 v43, v43
	v_rcp_f32_e32 v44, v44
	v_rcp_f32_e32 v45, v45
	v_pk_mul_f32 v[40:41], v[42:43], v[40:41]
	s_nop 0
	v_pk_mul_f32 v[32:33], v[32:33], v[40:41]
	v_pk_mul_f32 v[38:39], v[44:45], v[38:39]
	v_cvt_pk_bf16_f32 v32, v32, v33
	v_pk_mul_f32 v[34:35], v[34:35], v[38:39]
	s_nop 0
	v_cvt_pk_bf16_f32 v33, v34, v35
	global_store_dwordx2 v[66:67], v[32:33], off offset:1760
	ds_bpermute_b32 v32, v69, v224
	s_waitcnt lgkmcnt(0)
	v_add_f32_e32 v34, v224, v32
	ds_bpermute_b32 v35, v72, v34
	v_lshlrev_b64 v[32:33], 12, v[64:65]
	v_lshl_add_u64 v[32:33], s[18:19], 0, v[32:33]
	v_lshl_add_u64 v[32:33], v[32:33], 0, s[0:1]
	v_lshl_add_u64 v[32:33], v[32:33], 0, v[136:137]
	s_waitcnt lgkmcnt(0)
	v_add_f32_e32 v34, v34, v35
	v_rcp_f32_e32 v34, v34
	s_mov_b64 s[0:1], 0
	s_waitcnt vmcnt(15)
; __device__ __forceinline__ unsigned cvt_pk_bf16(float lo, float hi) { const f32x2 f = {lo, hi}; const bf16x2_t v = __builtin_convertvector(f, bf16x2_t); return __builtin_bit_cast(unsigned, v); }
; __device__ __forceinline__ float bflo(unsigned u) { return __uint_as_float(u << 16); }
; __device__ __forceinline__ float bfhi(unsigned u) { return __uint_as_float(u & 0xffff0000u); }
; __device__ __forceinline__ float rcp_f(float v) { return __builtin_amdgcn_rcpf(v); }
; __device__ __forceinline__ float silu_f(float v) { return v * rcp_f(1.f + __expf(-v)); }
; __device__ __forceinline__ void b_item(const Params& P, int layer, LAS unsigned char* lds, int item, int tid) {
;     ...
;     for (int u = 0; u < 2; ++u) {
;         float l = lrun[u]; l += __shfl_xor(l, 16); l += __shfl_xor(l, 32);
;         const float inv = rcp_f(l);
;         const size_t tok = tok0 + 64 * qc + 32 * th + 16 * u + c15;
;         const bf16_t* gate = pjp(proj, BG, 128, h, tok);
;         bf16_t* y = (bf16_t*)(P.ws + (layer == 0 ? WS_H : WS_D1)) + tok * DM + YB + h * 128;
; #pragma unroll
;         for (int vb = 0; vb < 8; ++vb) { const int v0 = 16 * vb + 4 * g; const u32x2 gt2 = *(const u32x2*)(gate + v0);
;             u32x2 o; o.x = cvt_pk_bf16(acco[u][vb][0] * inv * silu_f(bflo(gt2.x)), acco[u][vb][1] * inv * silu_f(bfhi(gt2.x)));
;             o.y = cvt_pk_bf16(acco[u][vb][2] * inv * silu_f(bflo(gt2.y)), acco[u][vb][3] * inv * silu_f(bfhi(gt2.y)));
;             *(u32x2*)(y + v0) = o; }
	v_lshlrev_b32_e32 v40, 16, v168
	v_and_b32_e32 v41, 0xffff0000, v168
	v_lshlrev_b32_e32 v38, 16, v169
	v_and_b32_e32 v39, 0xffff0000, v169
	v_mul_f32_e32 v35, 0xbfb8aa3b, v40
	v_mul_f32_e32 v42, 0xbfb8aa3b, v41
	v_mul_f32_e32 v43, 0xbfb8aa3b, v38
	v_mul_f32_e32 v44, 0xbfb8aa3b, v39
	v_exp_f32_e32 v35, v35
	v_exp_f32_e32 v42, v42
	v_exp_f32_e32 v43, v43
	v_exp_f32_e32 v44, v44
	v_add_f32_e32 v35, 1.0, v35
	v_add_f32_e32 v45, 1.0, v42
	v_add_f32_e32 v46, 1.0, v43
	v_add_f32_e32 v47, 1.0, v44
	v_rcp_f32_e32 v42, v35
	v_rcp_f32_e32 v43, v45
	v_rcp_f32_e32 v44, v46
	v_rcp_f32_e32 v45, v47
	v_pk_mul_f32 v[28:29], v[28:29], v[34:35] op_sel_hi:[1,0]
	v_pk_mul_f32 v[30:31], v[30:31], v[34:35] op_sel_hi:[1,0]
	v_pk_mul_f32 v[40:41], v[42:43], v[40:41]
	v_pk_mul_f32 v[38:39], v[44:45], v[38:39]
	v_pk_mul_f32 v[28:29], v[28:29], v[40:41]
	v_pk_mul_f32 v[30:31], v[30:31], v[38:39]
	v_cvt_pk_bf16_f32 v28, v28, v29
	v_cvt_pk_bf16_f32 v29, v30, v31
	global_store_dwordx2 v[32:33], v[28:29], off offset:1536
	s_waitcnt vmcnt(15)
	v_lshlrev_b32_e32 v30, 16, v170
	v_and_b32_e32 v31, 0xffff0000, v170
	v_lshlrev_b32_e32 v28, 16, v171
	v_and_b32_e32 v29, 0xffff0000, v171
	v_mul_f32_e32 v35, 0xbfb8aa3b, v30
	v_mul_f32_e32 v38, 0xbfb8aa3b, v31
	v_mul_f32_e32 v39, 0xbfb8aa3b, v28
	v_mul_f32_e32 v40, 0xbfb8aa3b, v29
	v_exp_f32_e32 v35, v35
	v_exp_f32_e32 v38, v38
	v_exp_f32_e32 v39, v39
	v_exp_f32_e32 v40, v40
	v_add_f32_e32 v35, 1.0, v35
	v_add_f32_e32 v41, 1.0, v38
	v_add_f32_e32 v42, 1.0, v39
	v_add_f32_e32 v43, 1.0, v40
	v_rcp_f32_e32 v38, v35
	v_rcp_f32_e32 v39, v41
	v_rcp_f32_e32 v40, v42
	v_rcp_f32_e32 v41, v43
	v_pk_mul_f32 v[24:25], v[24:25], v[34:35] op_sel_hi:[1,0]
	v_pk_mul_f32 v[26:27], v[26:27], v[34:35] op_sel_hi:[1,0]
	v_pk_mul_f32 v[30:31], v[38:39], v[30:31]
	v_pk_mul_f32 v[28:29], v[40:41], v[28:29]
	v_pk_mul_f32 v[24:25], v[24:25], v[30:31]
	v_pk_mul_f32 v[26:27], v[26:27], v[28:29]
	v_cvt_pk_bf16_f32 v24, v24, v25
	v_cvt_pk_bf16_f32 v25, v26, v27
	global_store_dwordx2 v[32:33], v[24:25], off offset:1568
	v_pk_mul_f32 v[20:21], v[20:21], v[34:35] op_sel_hi:[1,0]
	v_pk_mul_f32 v[22:23], v[22:23], v[34:35] op_sel_hi:[1,0]
	v_pk_mul_f32 v[16:17], v[16:17], v[34:35] op_sel_hi:[1,0]
	v_pk_mul_f32 v[18:19], v[18:19], v[34:35] op_sel_hi:[1,0]
	v_pk_mul_f32 v[12:13], v[12:13], v[34:35] op_sel_hi:[1,0]
	v_pk_mul_f32 v[14:15], v[14:15], v[34:35] op_sel_hi:[1,0]
	v_pk_mul_f32 v[8:9], v[8:9], v[34:35] op_sel_hi:[1,0]
	v_pk_mul_f32 v[10:11], v[10:11], v[34:35] op_sel_hi:[1,0]
	v_pk_mul_f32 v[4:5], v[4:5], v[34:35] op_sel_hi:[1,0]
	v_pk_mul_f32 v[6:7], v[6:7], v[34:35] op_sel_hi:[1,0]
	v_pk_mul_f32 v[0:1], v[0:1], v[34:35] op_sel_hi:[1,0]
	v_pk_mul_f32 v[2:3], v[2:3], v[34:35] op_sel_hi:[1,0]
	s_waitcnt vmcnt(15)
	v_lshlrev_b32_e32 v26, 16, v172
	v_and_b32_e32 v27, 0xffff0000, v172
	v_lshlrev_b32_e32 v24, 16, v173
	v_and_b32_e32 v25, 0xffff0000, v173
	v_mul_f32_e32 v28, 0xbfb8aa3b, v26
	v_mul_f32_e32 v29, 0xbfb8aa3b, v27
	v_mul_f32_e32 v30, 0xbfb8aa3b, v24
	v_mul_f32_e32 v31, 0xbfb8aa3b, v25
	v_exp_f32_e32 v28, v28
	v_exp_f32_e32 v29, v29
	v_exp_f32_e32 v30, v30
	v_exp_f32_e32 v31, v31
	v_add_f32_e32 v28, 1.0, v28
	v_add_f32_e32 v29, 1.0, v29
	v_add_f32_e32 v30, 1.0, v30
	v_add_f32_e32 v31, 1.0, v31
	v_rcp_f32_e32 v28, v28
	v_rcp_f32_e32 v29, v29
	v_rcp_f32_e32 v30, v30
	v_rcp_f32_e32 v31, v31
	v_pk_mul_f32 v[26:27], v[28:29], v[26:27]
	s_nop 0
	v_pk_mul_f32 v[20:21], v[20:21], v[26:27]
	v_pk_mul_f32 v[24:25], v[30:31], v[24:25]
	v_cvt_pk_bf16_f32 v20, v20, v21
	v_pk_mul_f32 v[22:23], v[22:23], v[24:25]
	s_nop 0
	v_cvt_pk_bf16_f32 v21, v22, v23
	global_store_dwordx2 v[32:33], v[20:21], off offset:1600
	s_waitcnt vmcnt(15)
; __device__ __forceinline__ unsigned cvt_pk_bf16(float lo, float hi) { const f32x2 f = {lo, hi}; const bf16x2_t v = __builtin_convertvector(f, bf16x2_t); return __builtin_bit_cast(unsigned, v); }
; __device__ __forceinline__ float bflo(unsigned u) { return __uint_as_float(u << 16); }
; __device__ __forceinline__ float bfhi(unsigned u) { return __uint_as_float(u & 0xffff0000u); }
; __device__ __forceinline__ float silu_f(float v) { return v * rcp_f(1.f + __expf(-v)); }
; __device__ __forceinline__ void b_item(const Params& P, int layer, LAS unsigned char* lds, int item, int tid) {
;     ...
;         for (int vb = 0; vb < 8; ++vb) { const int v0 = 16 * vb + 4 * g; const u32x2 gt2 = *(const u32x2*)(gate + v0);
;             u32x2 o; o.x = cvt_pk_bf16(acco[u][vb][0] * inv * silu_f(bflo(gt2.x)), acco[u][vb][1] * inv * silu_f(bfhi(gt2.x)));
;             o.y = cvt_pk_bf16(acco[u][vb][2] * inv * silu_f(bflo(gt2.y)), acco[u][vb][3] * inv * silu_f(bfhi(gt2.y)));
;             *(u32x2*)(y + v0) = o; }
	v_lshlrev_b32_e32 v22, 16, v174
	v_and_b32_e32 v23, 0xffff0000, v174
	v_lshlrev_b32_e32 v20, 16, v175
	v_and_b32_e32 v21, 0xffff0000, v175
	v_mul_f32_e32 v24, 0xbfb8aa3b, v22
	v_mul_f32_e32 v25, 0xbfb8aa3b, v23
	v_mul_f32_e32 v26, 0xbfb8aa3b, v20
	v_mul_f32_e32 v27, 0xbfb8aa3b, v21
	v_exp_f32_e32 v24, v24
	v_exp_f32_e32 v25, v25
	v_exp_f32_e32 v26, v26
	v_exp_f32_e32 v27, v27
	v_add_f32_e32 v24, 1.0, v24
	v_add_f32_e32 v25, 1.0, v25
	v_add_f32_e32 v26, 1.0, v26
	v_add_f32_e32 v27, 1.0, v27
	v_rcp_f32_e32 v24, v24
	v_rcp_f32_e32 v25, v25
	v_rcp_f32_e32 v26, v26
	v_rcp_f32_e32 v27, v27
	v_pk_mul_f32 v[22:23], v[24:25], v[22:23]
	s_nop 0
	v_pk_mul_f32 v[16:17], v[16:17], v[22:23]
	v_pk_mul_f32 v[20:21], v[26:27], v[20:21]
	v_cvt_pk_bf16_f32 v16, v16, v17
	v_pk_mul_f32 v[18:19], v[18:19], v[20:21]
	s_nop 0
	v_cvt_pk_bf16_f32 v17, v18, v19
	global_store_dwordx2 v[32:33], v[16:17], off offset:1632
	s_waitcnt vmcnt(15)
	v_lshlrev_b32_e32 v18, 16, v252
	v_and_b32_e32 v19, 0xffff0000, v252
	v_lshlrev_b32_e32 v16, 16, v253
	v_and_b32_e32 v17, 0xffff0000, v253
	v_mul_f32_e32 v20, 0xbfb8aa3b, v18
	v_mul_f32_e32 v21, 0xbfb8aa3b, v19
	v_mul_f32_e32 v22, 0xbfb8aa3b, v16
	v_mul_f32_e32 v23, 0xbfb8aa3b, v17
	v_exp_f32_e32 v20, v20
	v_exp_f32_e32 v21, v21
	v_exp_f32_e32 v22, v22
	v_exp_f32_e32 v23, v23
	v_add_f32_e32 v20, 1.0, v20
	v_add_f32_e32 v21, 1.0, v21
	v_add_f32_e32 v22, 1.0, v22
	v_add_f32_e32 v23, 1.0, v23
	v_rcp_f32_e32 v20, v20
	v_rcp_f32_e32 v21, v21
	v_rcp_f32_e32 v22, v22
	v_rcp_f32_e32 v23, v23
	v_pk_mul_f32 v[18:19], v[20:21], v[18:19]
	s_nop 0
	v_pk_mul_f32 v[12:13], v[12:13], v[18:19]
	v_pk_mul_f32 v[16:17], v[22:23], v[16:17]
	v_cvt_pk_bf16_f32 v12, v12, v13
	v_pk_mul_f32 v[14:15], v[14:15], v[16:17]
	s_nop 0
	v_cvt_pk_bf16_f32 v13, v14, v15
	global_store_dwordx2 v[32:33], v[12:13], off offset:1664
	s_waitcnt vmcnt(15)
	v_lshlrev_b32_e32 v14, 16, v254
	v_and_b32_e32 v15, 0xffff0000, v254
	v_lshlrev_b32_e32 v12, 16, v255
	v_and_b32_e32 v13, 0xffff0000, v255
	v_mul_f32_e32 v16, 0xbfb8aa3b, v14
	v_mul_f32_e32 v17, 0xbfb8aa3b, v15
	v_mul_f32_e32 v18, 0xbfb8aa3b, v12
	v_mul_f32_e32 v19, 0xbfb8aa3b, v13
	v_exp_f32_e32 v16, v16
	v_exp_f32_e32 v17, v17
	v_exp_f32_e32 v18, v18
	v_exp_f32_e32 v19, v19
	v_add_f32_e32 v16, 1.0, v16
	v_add_f32_e32 v17, 1.0, v17
	v_add_f32_e32 v18, 1.0, v18
	v_add_f32_e32 v19, 1.0, v19
	v_rcp_f32_e32 v16, v16
	v_rcp_f32_e32 v17, v17
	v_rcp_f32_e32 v18, v18
	v_rcp_f32_e32 v19, v19
	v_pk_mul_f32 v[14:15], v[16:17], v[14:15]
	s_nop 0
	v_pk_mul_f32 v[8:9], v[8:9], v[14:15]
	v_pk_mul_f32 v[12:13], v[18:19], v[12:13]
	v_cvt_pk_bf16_f32 v8, v8, v9
	v_pk_mul_f32 v[10:11], v[10:11], v[12:13]
	s_nop 0
	v_cvt_pk_bf16_f32 v9, v10, v11
	global_store_dwordx2 v[32:33], v[8:9], off offset:1696
	s_waitcnt vmcnt(15)
	v_lshlrev_b32_e32 v10, 16, v226
	v_and_b32_e32 v11, 0xffff0000, v226
	v_lshlrev_b32_e32 v8, 16, v227
	v_and_b32_e32 v9, 0xffff0000, v227
	v_mul_f32_e32 v12, 0xbfb8aa3b, v10
	v_mul_f32_e32 v13, 0xbfb8aa3b, v11
	v_mul_f32_e32 v14, 0xbfb8aa3b, v8
	v_mul_f32_e32 v15, 0xbfb8aa3b, v9
	v_exp_f32_e32 v12, v12
	v_exp_f32_e32 v13, v13
	v_exp_f32_e32 v14, v14
	v_exp_f32_e32 v15, v15
	v_add_f32_e32 v12, 1.0, v12
	v_add_f32_e32 v13, 1.0, v13
	v_add_f32_e32 v14, 1.0, v14
	v_add_f32_e32 v15, 1.0, v15
	v_rcp_f32_e32 v12, v12
	v_rcp_f32_e32 v13, v13
	v_rcp_f32_e32 v14, v14
	v_rcp_f32_e32 v15, v15
	v_pk_mul_f32 v[10:11], v[12:13], v[10:11]
	s_nop 0
	v_pk_mul_f32 v[4:5], v[4:5], v[10:11]
	v_pk_mul_f32 v[8:9], v[14:15], v[8:9]
	v_cvt_pk_bf16_f32 v4, v4, v5
	v_pk_mul_f32 v[6:7], v[6:7], v[8:9]
	s_nop 0
	v_cvt_pk_bf16_f32 v5, v6, v7
	global_store_dwordx2 v[32:33], v[4:5], off offset:1728
	s_waitcnt vmcnt(15)
	v_lshlrev_b32_e32 v6, 16, v250
	v_and_b32_e32 v7, 0xffff0000, v250
	v_lshlrev_b32_e32 v4, 16, v251
	v_and_b32_e32 v5, 0xffff0000, v251
	v_mul_f32_e32 v8, 0xbfb8aa3b, v6
	v_mul_f32_e32 v9, 0xbfb8aa3b, v7
	v_mul_f32_e32 v10, 0xbfb8aa3b, v4
	v_mul_f32_e32 v11, 0xbfb8aa3b, v5
	v_exp_f32_e32 v8, v8
	v_exp_f32_e32 v9, v9
	v_exp_f32_e32 v10, v10
	v_exp_f32_e32 v11, v11
	v_add_f32_e32 v8, 1.0, v8
	v_add_f32_e32 v9, 1.0, v9
	v_add_f32_e32 v10, 1.0, v10
	v_add_f32_e32 v11, 1.0, v11
	v_rcp_f32_e32 v8, v8
	v_rcp_f32_e32 v9, v9
	v_rcp_f32_e32 v10, v10
	v_rcp_f32_e32 v11, v11
	v_pk_mul_f32 v[6:7], v[8:9], v[6:7]
	s_nop 0
	v_pk_mul_f32 v[0:1], v[0:1], v[6:7]
	v_pk_mul_f32 v[4:5], v[10:11], v[4:5]
	v_cvt_pk_bf16_f32 v0, v0, v1
	v_pk_mul_f32 v[2:3], v[2:3], v[4:5]
	s_nop 0
	v_cvt_pk_bf16_f32 v1, v2, v3
	global_store_dwordx2 v[32:33], v[0:1], off offset:1760

; #define LAS __attribute__((address_space(3)))
; template <int ROWS, int CH>
; __device__ __forceinline__ void tile_load(LAS unsigned char* tile, const bf16_t* src, int ld, int tid) {
; #pragma unroll
;     for (int u = 0; u < ROWS * CH / 512; ++u) { const int i = tid + 512 * u, row = i / CH, ch = i % CH;
;         *(LAS u32x4*)(tile + off_b((unsigned)row, (unsigned)ch)) = *(const u32x4*)(src + (size_t)row * ld + ch * 8); }
; __device__ __forceinline__ void b_item(const Params& P, int layer, LAS unsigned char* lds, int item, int tid) {
;     const int b = item / 320, rem = item % 320, h = rem / 64, m = rem % 64, w = tid >> 6, lane = tid & 63;
;     const int qc = w >> 1, th = w & 1, g = lane >> 4, c15 = lane & 15;
;     const bf16_t* proj = (const bf16_t*)(P.ws + WS_PROJ);
;     const size_t tok0 = (size_t)b * SEQ + (size_t)m * 256;
;     LAS unsigned char* Qt = lds + 0; LAS unsigned char* KV = lds + 65536; LAS float* bias = (LAS float*)(lds + 131072);
;     tile_load<256, 16>(Qt, pjp(proj, BQ, 128, h, tok0), 128, tid);
;     for (int i = tid; i < 257; i += 512) bias[i] = P.rel_bias[(size_t)(layer * 5 + h) * 257 + i];
;     const int jst = (8 - 4 * m) > 0 ? (8 - 4 * m) : 0;
;     const long krow = (long)b * SEQ + (long)(4 * m - 8) * 64;
;     const bf16_t* kbase = pjp(proj, BKC, 128, h, 0) + krow * 128; const bf16_t* vbase = pjp(proj, BV, 128, h, 0) + krow * 128;
.LBB0_146:
	s_or_b64 exec, exec, s[0:1]
	v_mov_b32_e32 v0, s79
	s_waitcnt vmcnt(0) lgkmcnt(0)
	s_barrier
	ds_read_b32 v0, v0
	s_movk_i32 s0, 0x27f
	s_waitcnt lgkmcnt(0)
	s_barrier
	v_cmp_lt_i32_e32 vcc, s0, v0
	v_readfirstlane_b32 s10, v0
	s_mov_b64 s[0:1], -1
	s_cbranch_vccnz .LBB0_141
	s_mul_hi_i32 s0, s10, 0x66666667
	s_lshr_b32 s1, s0, 31
	s_ashr_i32 s0, s0, 7
	s_add_i32 s0, s0, s1
	s_mul_i32 s1, s0, 0x140
	s_sub_i32 s1, s10, s1
	s_bfe_u32 s10, s1, 0x60019
	s_add_i32 s11, s1, s10
	s_sext_i32_i16 s10, s11
	s_and_b32 s11, s11, 0xffc0
	s_sub_i32 s28, s1, s11
	s_ashr_i32 s1, s0, 31
	s_bfe_i64 s[50:51], s[28:29], 0x100000
	s_lshr_b32 s12, s10, 6
	s_ashr_i32 s10, s10, 6
	s_lshl_b64 s[14:15], s[0:1], 14
	s_lshl_b64 s[50:51], s[50:51], 8
	s_add_u32 s50, s50, s14
	s_addc_u32 s51, s51, s15
	s_bfe_i64 s[14:15], s[12:13], 0x100000
	s_lshl_b64 s[12:13], s[14:15], 15
	s_add_u32 s52, s50, s12
	s_addc_u32 s53, s51, s13
	s_lshl_b64 s[52:53], s[52:53], 8
	s_add_u32 s52, s60, s52
	s_addc_u32 s53, s61, s53
	v_lshl_add_u64 v[64:65], s[52:53], 0, v[96:97]
	v_lshl_add_u64 v[64:65], v[98:99], 1, v[64:65]
	global_load_dwordx4 v[64:67], v[64:65], off
	v_lshl_add_u64 v[68:69], s[52:53], 0, v[100:101]
	v_lshl_add_u64 v[68:69], v[102:103], 1, v[68:69]
	global_load_dwordx4 v[68:71], v[68:69], off
	v_lshl_add_u64 v[72:73], s[52:53], 0, v[104:105]
	v_lshl_add_u64 v[72:73], v[106:107], 1, v[72:73]
	global_load_dwordx4 v[72:75], v[72:73], off
	v_lshl_add_u64 v[76:77], s[52:53], 0, v[108:109]
	v_lshl_add_u64 v[76:77], v[110:111], 1, v[76:77]
	global_load_dwordx4 v[76:79], v[76:77], off
	v_lshl_add_u64 v[80:81], s[52:53], 0, v[112:113]
	v_lshl_add_u64 v[80:81], v[114:115], 1, v[80:81]
	global_load_dwordx4 v[80:83], v[80:81], off
	v_lshl_add_u64 v[84:85], s[52:53], 0, v[116:117]
	v_lshl_add_u64 v[84:85], v[118:119], 1, v[84:85]
	global_load_dwordx4 v[84:87], v[84:85], off
	v_lshl_add_u64 v[88:89], s[52:53], 0, v[120:121]
	v_lshl_add_u64 v[88:89], v[122:123], 1, v[88:89]
	global_load_dwordx4 v[88:91], v[88:89], off
	v_lshl_add_u64 v[92:93], s[52:53], 0, v[124:125]
	v_lshl_add_u64 v[92:93], v[126:127], 1, v[92:93]
	global_load_dwordx4 v[92:95], v[92:93], off
	s_and_saveexec_b64 s[52:53], s[42:43]
	s_cbranch_execz .LBB0_157
	s_mul_i32 s11, s84, 5
	s_add_i32 s65, s11, s10
	s_mul_hi_i32 s11, s65, 0x404
	s_mulk_i32 s65, 0x404
	s_mov_b64 s[56:57], -1
	v_mov_b32_e32 v0, v150
	v_mov_b32_e32 v1, v189
	s_and_saveexec_b64 s[54:55], s[44:45]
	s_cbranch_execz .LBB0_154
	s_add_u32 s56, s8, s65
	s_addc_u32 s57, s9, s11
	s_mov_b64 s[58:59], 0
	v_mov_b32_e32 v2, v208
	v_mov_b32_e32 v3, v210
	v_mov_b64_e32 v[0:1], v[150:151]

; #define LAS __attribute__((address_space(3)))
; __device__ __forceinline__ unsigned row_addr(int lane, int s) { return off_b((unsigned)(lane & 15), (unsigned)(4 * s + (lane >> 4))); }
; __device__ __forceinline__ void b_item(const Params& P, int layer, LAS unsigned char* lds, int item, int tid) {
;     ...
;     const int jst = (8 - 4 * m) > 0 ? (8 - 4 * m) : 0;
;     const long krow = (long)b * SEQ + (long)(4 * m - 8) * 64;
;     const bf16_t* kbase = pjp(proj, BKC, 128, h, 0) + krow * 128; const bf16_t* vbase = pjp(proj, BV, 128, h, 0) + krow * 128;
;     unsigned soff[2];
; #pragma unroll
;     for (int u = 0; u < 2; ++u) { const unsigned i = tid + 512 * u, row = i >> 4, ch = (i & 15) ^ (((row & 3u) << 2) | ((row >> 2) & 3u)); soff[u] = row * 128 + ch * 8; }
;     const unsigned ldsw = (unsigned)__builtin_amdgcn_readfirstlane(w) * 1024u;
;     ...
;     B_DMA(jst, 0);
;     __syncthreads();
;     LAS unsigned char* Qw = Qt + 4096 * (qc * 4 + th * 2);
;     float mrun[2] = {-1e30f, -1e30f}, lrun[2] = {0.f, 0.f}; const float bfar = bias[256];
;     unsigned kaddr[4], vaddr[8];
; #pragma unroll
;     for (int kk = 0; kk < 4; ++kk) kaddr[kk] = row_addr(lane, kk);
; #pragma unroll
;     for (int vb = 0; vb < 8; ++vb) vaddr[vb] = tr_addr<true>(lane, vb);
;     f32x4 acco[2][8];
; #pragma unroll
;     for (int u = 0; u < 2; ++u)
; #pragma unroll
;         for (int i = 0; i < 8; ++i) acco[u][i] = (f32x4){0.f, 0.f, 0.f, 0.f};
.LBB0_157:
	s_or_b64 exec, exec, s[52:53]
	s_sext_i32_i16 s11, s28
	s_lshl_b32 s52, s11, 2
	s_ashr_i32 s53, s52, 31
	s_sub_i32 s28, 8, s52
	s_lshl_b64 s[52:53], s[52:53], 13
	s_lshl_b64 s[0:1], s[0:1], 21
	s_add_u32 s0, s52, s0
	s_addc_u32 s1, s53, s1
	s_lshl_b64 s[0:1], s[0:1], 1
	s_lshl_b64 s[14:15], s[14:15], 23
	s_add_u32 s53, s39, s14
	s_addc_u32 s54, s62, s15
	s_cmp_lt_i32 s11, 2
	s_cselect_b32 s28, s28, 0
	s_add_u32 s11, s63, s14
	s_addc_u32 s14, s64, s15
	s_add_u32 s0, s0, 0xfffe0000
	s_addc_u32 s1, s1, -1
	s_add_u32 s11, s11, s0
	s_addc_u32 s52, s14, s1
	s_add_u32 s53, s53, s0
	v_readfirstlane_b32 s0, v190
	s_addc_u32 s54, s54, s1
	s_lshl_b32 s55, s0, 10
	s_lshl_b64 s[0:1], s[28:29], 14
	s_add_u32 s14, s11, s0
	s_addc_u32 s15, s52, s1
	s_add_i32 s56, s55, 0
	s_add_i32 s55, s56, 0x10000
	s_add_u32 s0, s53, s0
	s_addc_u32 s1, s54, s1
	s_add_i32 s57, s56, 0x14000
	v_lshl_add_u64 v[0:1], s[14:15], 0, v[158:159]
	s_mov_b32 m0, s55
	v_mov_b32_e32 v63, 0
	global_load_lds_dwordx4 v[0:1], off
	v_lshl_add_u64 v[0:1], s[0:1], 0, v[158:159]
	s_mov_b32 m0, s57
	v_mov_b32_e32 v62, v63
	global_load_lds_dwordx4 v[0:1], off
	v_lshl_add_u64 v[0:1], s[14:15], 0, v[160:161]
	s_add_i32 m0, s56, 0x12000
	v_mov_b32_e32 v61, v63
	global_load_lds_dwordx4 v[0:1], off
	v_lshl_add_u64 v[0:1], s[0:1], 0, v[160:161]
	s_add_i32 m0, s56, 0x16000
	s_cmp_gt_i32 s28, 11
	global_load_lds_dwordx4 v[0:1], off
	v_mov_b32_e32 v60, v63
	v_mov_b32_e32 v59, v63
	v_mov_b32_e32 v58, v63
	v_mov_b32_e32 v57, v63
	v_mov_b32_e32 v56, v63
	v_mov_b32_e32 v55, v63
	v_mov_b32_e32 v54, v63
	v_mov_b32_e32 v53, v63
	v_mov_b32_e32 v52, v63
	v_mov_b32_e32 v51, v63
	v_mov_b32_e32 v50, v63
	v_mov_b32_e32 v49, v63
	v_mov_b32_e32 v48, v63
	v_mov_b32_e32 v47, v63
	v_mov_b32_e32 v46, v63
	v_mov_b32_e32 v45, v63
	v_mov_b32_e32 v44, v63
	v_mov_b32_e32 v43, v63
	v_mov_b32_e32 v42, v63
	v_mov_b32_e32 v41, v63
	v_mov_b32_e32 v40, v63
	v_mov_b32_e32 v39, v63
	v_mov_b32_e32 v38, v63
	v_mov_b32_e32 v37, v63
	v_mov_b32_e32 v36, v63
	v_mov_b32_e32 v35, v63
	v_mov_b32_e32 v34, v63
	v_mov_b32_e32 v33, v63
	v_mov_b32_e32 v32, v63
	v_mov_b32_e32 v31, v63
	v_mov_b32_e32 v30, v63
	v_mov_b32_e32 v29, v63
	v_mov_b32_e32 v28, v63
	v_mov_b32_e32 v27, v63
	v_mov_b32_e32 v26, v63
	v_mov_b32_e32 v25, v63
	v_mov_b32_e32 v24, v63
	v_mov_b32_e32 v23, v63
	v_mov_b32_e32 v22, v63
	v_mov_b32_e32 v21, v63
	v_mov_b32_e32 v20, v63
	v_mov_b32_e32 v19, v63
	v_mov_b32_e32 v18, v63
	v_mov_b32_e32 v17, v63
	v_mov_b32_e32 v16, v63
	v_mov_b32_e32 v15, v63
	v_mov_b32_e32 v14, v63
	v_mov_b32_e32 v13, v63
	v_mov_b32_e32 v12, v63
	v_mov_b32_e32 v11, v63
	v_mov_b32_e32 v10, v63
	v_mov_b32_e32 v9, v63
	v_mov_b32_e32 v8, v63
	v_mov_b32_e32 v7, v63
	v_mov_b32_e32 v6, v63
	v_mov_b32_e32 v5, v63
	v_mov_b32_e32 v4, v63
	v_mov_b32_e32 v3, v63
	v_mov_b32_e32 v2, v63
	v_mov_b32_e32 v1, v63
	v_mov_b32_e32 v0, v63
	v_mov_b32_e32 v224, v63
	v_mov_b32_e32 v225, v63
	s_waitcnt vmcnt(4)
	ds_write_b128 v213, v[64:67]
	ds_write_b128 v214, v[68:71]
	ds_write_b128 v215, v[72:75]
	ds_write_b128 v216, v[76:79]
	ds_write_b128 v217, v[80:83]
	ds_write_b128 v218, v[84:87]
	ds_write_b128 v219, v[88:91]
	ds_write_b128 v220, v[92:95]
	s_waitcnt vmcnt(0) lgkmcnt(0)
	s_barrier
	s_cbranch_scc1 .LBB0_140
	v_mov_b32_e32 v0, s80
	ds_read_b32 v162, v0
	s_lshl_b32 s0, s28, 6
	v_mov_b32_e32 v225, 0
	v_subrev_u32_e32 v221, s28, v207
	v_subrev_u32_e32 v222, s0, v211
	v_subrev_u32_e32 v223, s0, v212
	s_waitcnt lgkmcnt(0)
	v_mov_b32_e32 v163, v162
	s_lshl_b32 s56, s28, 15
	s_add_i32 s57, s28, -1
	v_mov_b32_e32 v227, 0xf149f2ca
	v_mov_b32_e32 v224, 0
	v_mov_b32_e32 v226, 0xf149f2ca
	v_mov_b32_e32 v0, 0
	v_mov_b32_e32 v1, v225
	v_mov_b32_e32 v2, v225
	v_mov_b32_e32 v3, v225
	v_mov_b32_e32 v4, 0
	v_mov_b32_e32 v5, v225
	v_mov_b32_e32 v6, v225
	v_mov_b32_e32 v7, v225
	v_mov_b32_e32 v8, 0
	v_mov_b32_e32 v9, v225
	v_mov_b32_e32 v10, v225
	v_mov_b32_e32 v11, v225
	v_mov_b32_e32 v12, 0
	v_mov_b32_e32 v13, v225
	v_mov_b32_e32 v14, v225
	v_mov_b32_e32 v15, v225
	v_mov_b32_e32 v16, 0
	v_mov_b32_e32 v17, v225
	v_mov_b32_e32 v18, v225
	v_mov_b32_e32 v19, v225
	v_mov_b32_e32 v20, 0
	v_mov_b32_e32 v21, v225
	v_mov_b32_e32 v22, v225
	v_mov_b32_e32 v23, v225
	v_mov_b32_e32 v24, 0
	v_mov_b32_e32 v25, v225
	v_mov_b32_e32 v26, v225
	v_mov_b32_e32 v27, v225
	v_mov_b32_e32 v28, 0
	v_mov_b32_e32 v29, v225
	v_mov_b32_e32 v30, v225
	v_mov_b32_e32 v31, v225
	v_mov_b32_e32 v32, 0
	v_mov_b32_e32 v33, v225
	v_mov_b32_e32 v34, v225
	v_mov_b32_e32 v35, v225
	v_mov_b32_e32 v36, 0
	v_mov_b32_e32 v37, v225
	v_mov_b32_e32 v38, v225
	v_mov_b32_e32 v39, v225
	v_mov_b32_e32 v40, 0
	v_mov_b32_e32 v41, v225
	v_mov_b32_e32 v42, v225
	v_mov_b32_e32 v43, v225
	v_mov_b32_e32 v44, 0
	v_mov_b32_e32 v45, v225
	v_mov_b32_e32 v46, v225
	v_mov_b32_e32 v47, v225
	v_mov_b32_e32 v48, 0
	v_mov_b32_e32 v49, v225
	v_mov_b32_e32 v50, v225
	v_mov_b32_e32 v51, v225
	v_mov_b32_e32 v52, 0
	v_mov_b32_e32 v53, v225
	v_mov_b32_e32 v54, v225
	v_mov_b32_e32 v55, v225
	v_mov_b32_e32 v56, 0
	v_mov_b32_e32 v57, v225
	v_mov_b32_e32 v58, v225
	v_mov_b32_e32 v59, v225
	v_mov_b32_e32 v60, 0
	v_mov_b32_e32 v61, v225
	v_mov_b32_e32 v62, v225
	v_mov_b32_e32 v63, v225
	s_branch .LBB0_161
; __device__ __forceinline__ f32x4 mfma16(bf16x8 a, bf16x8 b, f32x4 c) { return __builtin_amdgcn_mfma_f32_16x16x32_bf16(a, b, c, 0, 0, 0); }
; __device__ __forceinline__ void b_item(const Params& P, int layer, LAS unsigned char* lds, int item, int tid) {
;     ...
;                 mt = fmaxf(mt, __shfl_xor(mt, 16)); mt = fmaxf(mt, __shfl_xor(mt, 32));
;                 const float mn = fmaxf(mrun[u], mt); alpha[u] = __expf(mrun[u] - mn); mrun[u] = mn;
;                 float ls = 0.f;
; #pragma unroll
;                 for (int sb = 0; sb < 4; ++sb)
; #pragma unroll
;                     for (int r = 0; r < 4; ++r) { const float pe = __expf(accs[u][sb][r] - mn); accs[u][sb][r] = pe; ls += pe; }
;                 lrun[u] = lrun[u] * alpha[u] + ls;
;                 pf[u][0] = pack8(accs[u][0], accs[u][1]); pf[u][1] = pack8(accs[u][2], accs[u][3]); }
;             __builtin_amdgcn_s_setprio(1);
; #pragma unroll
;             for (int vb = 0; vb < 8; ++vb) { acco[0][vb] = acco[0][vb] * alpha[0]; acco[1][vb] = acco[1][vb] * alpha[1];
; #pragma unroll
;                 for (int ks = 0; ks < 2; ++ks) { const bf16x8 vf = tr_frag_a<true>(Vt, vaddr[vb], ks);
;                     acco[0][vb] = mfma16(vf, pf[0][ks], acco[0][vb]); acco[1][vb] = mfma16(vf, pf[1][ks], acco[1][vb]); } }
.LBB0_159:
	s_or_b64 exec, exec, s[0:1]
	s_waitcnt lgkmcnt(0)
	v_max3_f32 v81, v227, v80, v81
	v_sub_f32_e32 v69, v92, v81
	v_mul_f32_e32 v69, 0x3fb8aa3b, v69
	v_exp_f32_e32 v70, v69
	v_sub_f32_e32 v69, v93, v81
	v_mul_f32_e32 v69, 0x3fb8aa3b, v69
	v_exp_f32_e32 v71, v69
	v_sub_f32_e32 v69, v94, v81
	v_sub_f32_e32 v64, v227, v81
	v_mul_f32_e32 v69, 0x3fb8aa3b, v69
	v_mul_f32_e32 v64, 0x3fb8aa3b, v64
	v_exp_f32_e32 v92, v69
	v_sub_f32_e32 v69, v95, v81
	v_exp_f32_e32 v80, v64
	v_sub_f32_e32 v64, v164, v81
	v_mul_f32_e32 v69, 0x3fb8aa3b, v69
	v_mul_f32_e32 v64, 0x3fb8aa3b, v64
	v_sub_f32_e32 v65, v165, v81
	v_exp_f32_e32 v93, v69
	v_sub_f32_e32 v69, v88, v81
	v_exp_f32_e32 v64, v64
	v_mul_f32_e32 v65, 0x3fb8aa3b, v65
	v_sub_f32_e32 v66, v166, v81
	v_mul_f32_e32 v69, 0x3fb8aa3b, v69
	v_exp_f32_e32 v65, v65
	v_mul_f32_e32 v66, 0x3fb8aa3b, v66
	v_sub_f32_e32 v67, v167, v81
	v_exp_f32_e32 v88, v69
	v_sub_f32_e32 v69, v89, v81
	v_exp_f32_e32 v66, v66
	v_mul_f32_e32 v67, 0x3fb8aa3b, v67
	v_mul_f32_e32 v69, 0x3fb8aa3b, v69
	v_exp_f32_e32 v67, v67
	v_exp_f32_e32 v89, v69
	v_sub_f32_e32 v69, v90, v81
	v_add_f32_e32 v68, 0, v64
	v_mul_f32_e32 v69, 0x3fb8aa3b, v69
	v_add_f32_e32 v68, v65, v68
	v_exp_f32_e32 v90, v69
	v_sub_f32_e32 v69, v91, v81
	v_add_f32_e32 v68, v66, v68
	v_mul_f32_e32 v69, 0x3fb8aa3b, v69
	v_add_f32_e32 v68, v67, v68
	v_exp_f32_e32 v91, v69
	v_sub_f32_e32 v69, v84, v81
	v_add_f32_e32 v68, v70, v68
	v_mul_f32_e32 v69, 0x3fb8aa3b, v69
	v_add_f32_e32 v68, v71, v68
	v_exp_f32_e32 v84, v69
	v_sub_f32_e32 v69, v85, v81
	v_add_f32_e32 v68, v92, v68
	v_mul_f32_e32 v69, 0x3fb8aa3b, v69
	v_add_f32_e32 v68, v93, v68
	v_exp_f32_e32 v85, v69
	v_sub_f32_e32 v69, v86, v81
	v_add_f32_e32 v68, v88, v68
	v_mul_f32_e32 v69, 0x3fb8aa3b, v69
	v_add_f32_e32 v68, v89, v68
	v_exp_f32_e32 v86, v69
	v_sub_f32_e32 v69, v87, v81
	v_add_f32_e32 v68, v90, v68
	v_mul_f32_e32 v69, 0x3fb8aa3b, v69
	ds_bpermute_b32 v82, v82, v229
	v_add_f32_e32 v68, v91, v68
	v_exp_f32_e32 v87, v69
	v_add_f32_e32 v68, v84, v68
	v_add_f32_e32 v68, v85, v68
	v_add_f32_e32 v68, v86, v68
	v_add_f32_e32 v83, v87, v68
	v_cvt_pk_bf16_f32 v68, v64, v65
	s_waitcnt lgkmcnt(0)
	v_max_f32_e32 v64, v82, v82
	v_max_f32_e32 v65, v229, v229
	v_max_f32_e32 v82, v65, v64
	v_cvt_pk_bf16_f32 v70, v70, v71
	v_cvt_pk_bf16_f32 v71, v92, v93
	ds_bpermute_b32 v92, v228, v82
	v_cvt_pk_bf16_f32 v69, v66, v67
	v_cvt_pk_bf16_f32 v66, v84, v85
	v_cvt_pk_bf16_f32 v67, v86, v87
	v_cvt_pk_bf16_f32 v64, v88, v89
	s_waitcnt lgkmcnt(0)
	v_max3_f32 v84, v226, v82, v92
	v_sub_f32_e32 v85, v168, v84
	v_mul_f32_e32 v85, 0x3fb8aa3b, v85
	v_exp_f32_e32 v86, v85
	v_sub_f32_e32 v85, v169, v84
	v_mul_f32_e32 v85, 0x3fb8aa3b, v85
	v_exp_f32_e32 v87, v85
	v_sub_f32_e32 v85, v170, v84
	v_sub_f32_e32 v76, v76, v84
	v_mul_f32_e32 v85, 0x3fb8aa3b, v85
	v_mul_f32_e32 v76, 0x3fb8aa3b, v76
	v_cvt_pk_bf16_f32 v65, v90, v91
	v_exp_f32_e32 v88, v85
	v_sub_f32_e32 v85, v171, v84
	v_exp_f32_e32 v90, v76
	v_sub_f32_e32 v76, v77, v84
	v_mul_f32_e32 v85, 0x3fb8aa3b, v85
	v_mul_f32_e32 v76, 0x3fb8aa3b, v76
	v_exp_f32_e32 v89, v85
	v_exp_f32_e32 v91, v76
	v_sub_f32_e32 v76, v78, v84
	v_add_f32_e32 v85, 0, v86
	v_mul_f32_e32 v76, 0x3fb8aa3b, v76
	v_add_f32_e32 v85, v87, v85
	v_exp_f32_e32 v92, v76
	v_sub_f32_e32 v76, v79, v84
	v_add_f32_e32 v85, v88, v85
	v_mul_f32_e32 v76, 0x3fb8aa3b, v76
	v_sub_f32_e32 v72, v72, v84
	v_add_f32_e32 v85, v89, v85
	v_exp_f32_e32 v79, v76
	v_mul_f32_e32 v72, 0x3fb8aa3b, v72
	v_sub_f32_e32 v73, v73, v84
	v_sub_f32_e32 v77, v172, v84
	v_add_f32_e32 v76, v90, v85
	v_exp_f32_e32 v72, v72
	v_mul_f32_e32 v73, 0x3fb8aa3b, v73
	v_sub_f32_e32 v74, v74, v84
	v_mul_f32_e32 v77, 0x3fb8aa3b, v77
	v_add_f32_e32 v76, v91, v76
	v_exp_f32_e32 v73, v73
	v_mul_f32_e32 v74, 0x3fb8aa3b, v74
	v_sub_f32_e32 v75, v75, v84
	v_exp_f32_e32 v93, v77
	v_sub_f32_e32 v77, v173, v84
	v_add_f32_e32 v76, v92, v76
	v_exp_f32_e32 v74, v74
	v_mul_f32_e32 v75, 0x3fb8aa3b, v75
	v_mul_f32_e32 v77, 0x3fb8aa3b, v77
	v_add_f32_e32 v76, v79, v76
	v_exp_f32_e32 v75, v75
	v_exp_f32_e32 v94, v77
	v_sub_f32_e32 v77, v174, v84
	v_add_f32_e32 v76, v72, v76
	v_mul_f32_e32 v77, 0x3fb8aa3b, v77
	v_add_f32_e32 v76, v73, v76
	v_exp_f32_e32 v95, v77
	v_sub_f32_e32 v77, v175, v84
	v_sub_f32_e32 v82, v226, v84
	v_add_f32_e32 v76, v74, v76
	v_mul_f32_e32 v77, 0x3fb8aa3b, v77
	v_mul_f32_e32 v82, 0x3fb8aa3b, v82
	v_add_f32_e32 v76, v75, v76
	v_exp_f32_e32 v164, v77
	v_exp_f32_e32 v82, v82
	v_add_f32_e32 v76, v93, v76
	v_add_f32_e32 v76, v94, v76
	v_add_f32_e32 v76, v95, v76
	v_add_f32_e32 v85, v164, v76
	v_fmac_f32_e32 v83, v225, v80
	v_fmac_f32_e32 v85, v224, v82
	v_cvt_pk_bf16_f32 v76, v86, v87
	v_cvt_pk_bf16_f32 v77, v88, v89
	v_cvt_pk_bf16_f32 v78, v90, v91
	v_cvt_pk_bf16_f32 v79, v92, v79
	v_cvt_pk_bf16_f32 v72, v72, v73
	v_cvt_pk_bf16_f32 v73, v74, v75
	v_cvt_pk_bf16_f32 v74, v93, v94
	v_cvt_pk_bf16_f32 v75, v95, v164
	s_setprio 1
	v_add3_u32 v90, s28, v198, v197
	ds_read_b64_tr_b16 v[86:87], v90 offset:16384
	ds_read_b64_tr_b16 v[88:89], v90 offset:20480
	v_pk_mul_f32 v[62:63], v[62:63], v[80:81] op_sel_hi:[1,0]
	v_pk_mul_f32 v[60:61], v[60:61], v[80:81] op_sel_hi:[1,0]
	v_pk_mul_f32 v[30:31], v[30:31], v[82:83] op_sel_hi:[1,0]
	v_pk_mul_f32 v[28:29], v[28:29], v[82:83] op_sel_hi:[1,0]
	s_waitcnt lgkmcnt(0)
; __device__ __forceinline__ f32x4 mfma16(bf16x8 a, bf16x8 b, f32x4 c) { return __builtin_amdgcn_mfma_f32_16x16x32_bf16(a, b, c, 0, 0, 0); }
; __device__ __forceinline__ void b_item(const Params& P, int layer, LAS unsigned char* lds, int item, int tid) {
;     ...
;             __builtin_amdgcn_s_setprio(1);
; #pragma unroll
;             for (int vb = 0; vb < 8; ++vb) { acco[0][vb] = acco[0][vb] * alpha[0]; acco[1][vb] = acco[1][vb] * alpha[1];
; #pragma unroll
;                 for (int ks = 0; ks < 2; ++ks) { const bf16x8 vf = tr_frag_a<true>(Vt, vaddr[vb], ks);
;                     acco[0][vb] = mfma16(vf, pf[0][ks], acco[0][vb]); acco[1][vb] = mfma16(vf, pf[1][ks], acco[1][vb]); } }
;             __builtin_amdgcn_s_setprio(0);
	v_mfma_f32_16x16x32_bf16 v[60:63], v[86:89], v[68:71], v[60:63]
	v_mul_f32_e64 v58, v58, v80
	v_mul_f32_e64 v59, v59, v80
	v_pk_mul_f32 v[56:57], v[56:57], v[80:81] op_sel_hi:[1,0]
	v_pk_mul_f32 v[26:27], v[26:27], v[82:83] op_sel_hi:[1,0]
	v_mfma_f32_16x16x32_bf16 v[28:31], v[86:89], v[76:79], v[28:31]
	ds_read_b64_tr_b16 v[86:87], v90 offset:24576
	ds_read_b64_tr_b16 v[88:89], v90 offset:28672
	v_add3_u32 v90, s28, v199, v197
	v_pk_mul_f32 v[24:25], v[24:25], v[82:83] op_sel_hi:[1,0]
	s_waitcnt lgkmcnt(0)
	v_mfma_f32_16x16x32_bf16 v[60:63], v[86:89], v[64:67], v[60:63]
	v_mul_f32_e64 v54, v54, v80
	v_mul_f32_e64 v55, v55, v80
	v_pk_mul_f32 v[52:53], v[52:53], v[80:81] op_sel_hi:[1,0]
	v_pk_mul_f32 v[22:23], v[22:23], v[82:83] op_sel_hi:[1,0]
	v_mfma_f32_16x16x32_bf16 v[28:31], v[86:89], v[72:75], v[28:31]
	ds_read_b64_tr_b16 v[86:87], v90 offset:16384
	ds_read_b64_tr_b16 v[88:89], v90 offset:20480
	v_pk_mul_f32 v[20:21], v[20:21], v[82:83] op_sel_hi:[1,0]
	v_pk_mul_f32 v[50:51], v[50:51], v[80:81] op_sel_hi:[1,0]
	s_waitcnt lgkmcnt(0)
	v_mfma_f32_16x16x32_bf16 v[56:59], v[86:89], v[68:71], v[56:59]
	v_mul_f32_e64 v48, v48, v80
	v_mul_f32_e64 v49, v49, v80
	v_pk_mul_f32 v[18:19], v[18:19], v[82:83] op_sel_hi:[1,0]
	v_pk_mul_f32 v[16:17], v[16:17], v[82:83] op_sel_hi:[1,0]
	v_mfma_f32_16x16x32_bf16 v[24:27], v[86:89], v[76:79], v[24:27]
	ds_read_b64_tr_b16 v[86:87], v90 offset:24576
	ds_read_b64_tr_b16 v[88:89], v90 offset:28672
	v_add3_u32 v90, s28, v200, v197
	v_pk_mul_f32 v[46:47], v[46:47], v[80:81] op_sel_hi:[1,0]
	s_waitcnt lgkmcnt(0)
	v_mfma_f32_16x16x32_bf16 v[56:59], v[86:89], v[64:67], v[56:59]
	v_mul_f32_e64 v44, v44, v80
	v_mul_f32_e64 v45, v45, v80
	v_pk_mul_f32 v[14:15], v[14:15], v[82:83] op_sel_hi:[1,0]
	v_pk_mul_f32 v[12:13], v[12:13], v[82:83] op_sel_hi:[1,0]
	v_mfma_f32_16x16x32_bf16 v[24:27], v[86:89], v[72:75], v[24:27]
	ds_read_b64_tr_b16 v[86:87], v90 offset:16384
	ds_read_b64_tr_b16 v[88:89], v90 offset:20480
	v_pk_mul_f32 v[42:43], v[42:43], v[80:81] op_sel_hi:[1,0]
	v_pk_mul_f32 v[40:41], v[40:41], v[80:81] op_sel_hi:[1,0]
	s_waitcnt lgkmcnt(0)
	v_mfma_f32_16x16x32_bf16 v[52:55], v[86:89], v[68:71], v[52:55]
	v_mul_f32_e64 v10, v10, v82
	v_mul_f32_e64 v11, v11, v82
	v_pk_mul_f32 v[8:9], v[8:9], v[82:83] op_sel_hi:[1,0]
	v_pk_mul_f32 v[38:39], v[38:39], v[80:81] op_sel_hi:[1,0]
	v_mfma_f32_16x16x32_bf16 v[20:23], v[86:89], v[76:79], v[20:23]
	ds_read_b64_tr_b16 v[86:87], v90 offset:24576
	ds_read_b64_tr_b16 v[88:89], v90 offset:28672
	v_add3_u32 v90, s28, v201, v197
	v_pk_mul_f32 v[36:37], v[36:37], v[80:81] op_sel_hi:[1,0]
	s_waitcnt lgkmcnt(0)
	v_mfma_f32_16x16x32_bf16 v[52:55], v[86:89], v[64:67], v[52:55]
	v_mul_f32_e64 v6, v6, v82
	v_mul_f32_e64 v7, v7, v82
	v_pk_mul_f32 v[4:5], v[4:5], v[82:83] op_sel_hi:[1,0]
	v_pk_mul_f32 v[34:35], v[34:35], v[80:81] op_sel_hi:[1,0]
	v_mfma_f32_16x16x32_bf16 v[20:23], v[86:89], v[72:75], v[20:23]
	ds_read_b64_tr_b16 v[86:87], v90 offset:16384
	ds_read_b64_tr_b16 v[88:89], v90 offset:20480
	v_pk_mul_f32 v[32:33], v[32:33], v[80:81] op_sel_hi:[1,0]
	v_add3_u32 v80, s28, v205, v197
	s_waitcnt lgkmcnt(0)
	v_mfma_f32_16x16x32_bf16 v[48:51], v[86:89], v[68:71], v[48:51]
	v_mul_f32_e64 v2, v2, v82
	v_mul_f32_e64 v3, v3, v82
	v_pk_mul_f32 v[0:1], v[0:1], v[82:83] op_sel_hi:[1,0]
	v_mfma_f32_16x16x32_bf16 v[16:19], v[86:89], v[76:79], v[16:19]
	ds_read_b64_tr_b16 v[86:87], v90 offset:24576
	ds_read_b64_tr_b16 v[88:89], v90 offset:28672
	v_add3_u32 v90, s28, v202, v197
	s_waitcnt lgkmcnt(0)
	v_mfma_f32_16x16x32_bf16 v[48:51], v[86:89], v[64:67], v[48:51]
	v_mfma_f32_16x16x32_bf16 v[16:19], v[86:89], v[72:75], v[16:19]
	ds_read_b64_tr_b16 v[86:87], v90 offset:16384
	ds_read_b64_tr_b16 v[88:89], v90 offset:20480
	s_waitcnt lgkmcnt(0)
	v_mfma_f32_16x16x32_bf16 v[44:47], v[86:89], v[68:71], v[44:47]
	v_mfma_f32_16x16x32_bf16 v[12:15], v[86:89], v[76:79], v[12:15]
	ds_read_b64_tr_b16 v[86:87], v90 offset:24576
	ds_read_b64_tr_b16 v[88:89], v90 offset:28672
	v_add3_u32 v90, s28, v203, v197
	s_waitcnt lgkmcnt(0)
	v_mfma_f32_16x16x32_bf16 v[44:47], v[86:89], v[64:67], v[44:47]
	v_mfma_f32_16x16x32_bf16 v[12:15], v[86:89], v[72:75], v[12:15]
	ds_read_b64_tr_b16 v[86:87], v90 offset:16384
	ds_read_b64_tr_b16 v[88:89], v90 offset:20480
	s_waitcnt lgkmcnt(0)
	v_mfma_f32_16x16x32_bf16 v[40:43], v[86:89], v[68:71], v[40:43]
	v_mfma_f32_16x16x32_bf16 v[8:11], v[86:89], v[76:79], v[8:11]
	ds_read_b64_tr_b16 v[86:87], v90 offset:24576
	ds_read_b64_tr_b16 v[88:89], v90 offset:28672
	v_add3_u32 v90, s28, v204, v197
	s_waitcnt lgkmcnt(0)
	v_mfma_f32_16x16x32_bf16 v[40:43], v[86:89], v[64:67], v[40:43]
	v_mfma_f32_16x16x32_bf16 v[8:11], v[86:89], v[72:75], v[8:11]
	ds_read_b64_tr_b16 v[86:87], v90 offset:16384
	ds_read_b64_tr_b16 v[88:89], v90 offset:20480
	s_waitcnt lgkmcnt(0)
	v_mfma_f32_16x16x32_bf16 v[36:39], v[86:89], v[68:71], v[36:39]
	v_mfma_f32_16x16x32_bf16 v[4:7], v[86:89], v[76:79], v[4:7]
	ds_read_b64_tr_b16 v[86:87], v90 offset:24576
	ds_read_b64_tr_b16 v[88:89], v90 offset:28672
	s_waitcnt lgkmcnt(0)
	v_mfma_f32_16x16x32_bf16 v[36:39], v[86:89], v[64:67], v[36:39]
	v_mfma_f32_16x16x32_bf16 v[4:7], v[86:89], v[72:75], v[4:7]
	ds_read_b64_tr_b16 v[86:87], v80 offset:16384
	ds_read_b64_tr_b16 v[88:89], v80 offset:20480
	s_waitcnt lgkmcnt(0)
	v_mfma_f32_16x16x32_bf16 v[32:35], v[86:89], v[68:71], v[32:35]
	ds_read_b64_tr_b16 v[68:69], v80 offset:24576
	ds_read_b64_tr_b16 v[70:71], v80 offset:28672
	v_mfma_f32_16x16x32_bf16 v[0:3], v[86:89], v[76:79], v[0:3]
	s_waitcnt lgkmcnt(0)
	v_mfma_f32_16x16x32_bf16 v[32:35], v[68:71], v[64:67], v[32:35]
	v_mfma_f32_16x16x32_bf16 v[0:3], v[68:71], v[72:75], v[0:3]
	s_setprio 0
	v_mov_b32_e32 v227, v81
	v_mov_b32_e32 v226, v84
	v_mov_b32_e32 v224, v85
	v_mov_b32_e32 v225, v83

; __global__ __launch_bounds__(512, 2) void hybrid_fwd(Params P0) {
	.amdhsa_kernel _Z10hybrid_fwd6Params
		.amdhsa_group_segment_fixed_size 0
		.amdhsa_private_segment_fixed_size 0
		.amdhsa_kernarg_size 344
		.amdhsa_user_sgpr_count 2
		.amdhsa_user_sgpr_dispatch_ptr 0
		.amdhsa_user_sgpr_queue_ptr 0
		.amdhsa_user_sgpr_kernarg_segment_ptr 1
		.amdhsa_user_sgpr_dispatch_id 0
		.amdhsa_user_sgpr_kernarg_preload_length 0
		.amdhsa_user_sgpr_kernarg_preload_offset 0
		.amdhsa_user_sgpr_private_segment_size 0
		.amdhsa_uses_dynamic_stack 0
		.amdhsa_enable_private_segment 0
		.amdhsa_system_sgpr_workgroup_id_x 1
		.amdhsa_system_sgpr_workgroup_id_y 0
		.amdhsa_system_sgpr_workgroup_id_z 0
		.amdhsa_system_sgpr_workgroup_info 0
		.amdhsa_system_vgpr_workitem_id 2
		.amdhsa_next_free_vgpr 256
		.amdhsa_next_free_sgpr 100
		.amdhsa_accum_offset 256
		.amdhsa_reserve_vcc 1
		.amdhsa_float_round_mode_32 0
		.amdhsa_float_round_mode_16_64 0
		.amdhsa_float_denorm_mode_32 3
		.amdhsa_float_denorm_mode_16_64 3
		.amdhsa_dx10_clamp 1
		.amdhsa_ieee_mode 1
		.amdhsa_fp16_overflow 0
		.amdhsa_tg_split 0
		.amdhsa_exception_fp_ieee_invalid_op 0
		.amdhsa_exception_fp_denorm_src 0
		.amdhsa_exception_fp_ieee_div_zero 0
		.amdhsa_exception_fp_ieee_overflow 0
		.amdhsa_exception_fp_ieee_underflow 0
		.amdhsa_exception_fp_ieee_inexact 0
		.amdhsa_exception_int_div_zero 0
	.end_amdhsa_kernel

; __global__ __launch_bounds__(512, 2) void hybrid_fwd(Params P0) {
amdhsa.kernels:
  - .agpr_count:     0
    .args:
      - .offset:         0
        .size:           88
        .value_kind:     by_value
      - .offset:         88
        .size:           4
        .value_kind:     hidden_block_count_x
      - .offset:         92
        .size:           4
        .value_kind:     hidden_block_count_y
      - .offset:         96
        .size:           4
        .value_kind:     hidden_block_count_z
      - .offset:         100
        .size:           2
        .value_kind:     hidden_group_size_x
      - .offset:         102
        .size:           2
        .value_kind:     hidden_group_size_y
      - .offset:         104
        .size:           2
        .value_kind:     hidden_group_size_z
      - .offset:         106
        .size:           2
        .value_kind:     hidden_remainder_x
      - .offset:         108
        .size:           2
        .value_kind:     hidden_remainder_y
      - .offset:         110
        .size:           2
        .value_kind:     hidden_remainder_z
      - .offset:         128
        .size:           8
        .value_kind:     hidden_global_offset_x
      - .offset:         136
        .size:           8
        .value_kind:     hidden_global_offset_y
      - .offset:         144
        .size:           8
        .value_kind:     hidden_global_offset_z
      - .offset:         152
        .size:           2
        .value_kind:     hidden_grid_dims
      - .offset:         176
        .size:           8
        .value_kind:     hidden_multigrid_sync_arg
      - .offset:         208
        .size:           4
        .value_kind:     hidden_dynamic_lds_size
    .group_segment_fixed_size: 0
    .kernarg_segment_align: 8
    .kernarg_segment_size: 344
    .language:       OpenCL C
    .language_version:
      - 2
      - 0
    .max_flat_workgroup_size: 512
    .name:           _Z10hybrid_fwd6Params
    .private_segment_fixed_size: 0
    .sgpr_count:     106
    .sgpr_spill_count: 204
    .symbol:         _Z10hybrid_fwd6Params.kd
    .uniform_work_group_size: 1
    .uses_dynamic_stack: false
    .vgpr_count:     256
    .vgpr_spill_count: 0
    .wavefront_size: 64
